# short-conv item: four halo-row loads issued together instead of three dependent round trips
# speedup vs baseline: 1.0072x; 1.0045x over previous
; __device__ __forceinline__ int get_tid() { int t = threadIdx.x; asm volatile("" : "+v"(t)); return t; }
; __device__ __forceinline__ void unpack8(const u32x4 w, float (&f)[8]) { f[0] = bflo(w.x); f[1] = bfhi(w.x); f[2] = bflo(w.y); f[3] = bfhi(w.y); f[4] = bflo(w.z); f[5] = bfhi(w.z); f[6] = bflo(w.w); f[7] = bfhi(w.w); }
; __device__ __forceinline__ void sc_item(const Params& P, int l, int si) {
;     ...
;     const int tid = get_tid(), cgi = tid & 63, run = tid >> 6, c0 = cgi * 8, t0 = si * 128 + run * 16;
;     const float* cw = P.sc_conv_w + (size_t)l * 3 * 512;
;     float w0[8], w1[8], w2[8];
; #pragma unroll
;     for (int j = 0; j < 8; ++j) { w0[j] = cw[c0 + j]; w1[j] = cw[512 + c0 + j]; w2[j] = cw[1024 + c0 + j]; }
;     float p1[8], p2[8];
;     if ((t0 & 2047) != 0) {
;         float a[8], b[8];
;         unpack8(*(const u32x4*)(Z + (size_t)(t0 - 1) * ZC + ZSC + c0), a); unpack8(*(const u32x4*)(Z + (size_t)(t0 - 1) * ZC + ZSX + c0), b);
; #pragma unroll
;         for (int j = 0; j < 8; ++j) p1[j] = a[j] * b[j];
;         unpack8(*(const u32x4*)(Z + (size_t)(t0 - 2) * ZC + ZSC + c0), a); unpack8(*(const u32x4*)(Z + (size_t)(t0 - 2) * ZC + ZSX + c0), b);
; #pragma unroll
;         for (int j = 0; j < 8; ++j) p2[j] = a[j] * b[j];
;     } else {
; #pragma unroll
;         for (int j = 0; j < 8; ++j) { p1[j] = 0.f; p2[j] = 0.f; } }
.LBB0_518:
	s_cmpk_gt_i32 s2, 0x5ff
	s_mov_b64 s[30:31], -1
	s_cbranch_scc0 .LBB0_528
	v_mov_b32_e32 v26, v0
	s_mov_b64 s[4:5], 0x1000
	v_lshlrev_b32_e32 v2, 3, v26
	v_and_b32_e32 v28, 0x1f8, v2
	v_lshlrev_b32_e32 v194, 2, v28
	v_lshl_add_u64 v[18:19], s[38:39], 0, v[194:195]
	global_load_dwordx4 v[2:5], v194, s[38:39] offset:16
	global_load_dwordx4 v[6:9], v194, s[38:39]
	global_load_dwordx4 v[10:13], v194, s[38:39] offset:2064
	global_load_dwordx4 v[14:17], v194, s[38:39] offset:2048
	v_lshl_add_u64 v[22:23], v[18:19], 0, s[4:5]
	v_add_co_u32_e32 v18, vcc, 0x1000, v18
	v_ashrrev_i32_e32 v27, 2, v26
	s_nop 0
	v_addc_co_u32_e32 v19, vcc, 0, v19, vcc
	global_load_dwordx4 v[18:21], v[18:19], off
	s_nop 0
	global_load_dwordx4 v[22:25], v[22:23], off offset:16
	s_lshl_b32 s4, s2, 7
	v_and_b32_e32 v27, -16, v27
	s_add_i32 s4, s4, 0xfffd0000
	v_add_u32_e32 v27, s4, v27
	v_and_b32_e32 v29, 0x7f0, v27
	v_mov_b32_e32 v194, v195
	v_cmp_ne_u32_e32 vcc, 0, v29
	v_mov_b64_e32 v[38:39], v[194:195]
	v_mov_b64_e32 v[106:107], v[194:195]
	v_mov_b64_e32 v[42:43], v[194:195]
	v_mov_b64_e32 v[104:105], v[194:195]
	v_mov_b64_e32 v[52:53], v[194:195]
	v_mov_b64_e32 v[50:51], v[194:195]
	v_mov_b64_e32 v[48:49], v[194:195]
	v_mov_b64_e32 v[46:47], v[194:195]
	s_and_saveexec_b64 s[30:31], vcc
	s_cbranch_execz .LBB0_521
	v_add_u32_e32 v29, -1, v27
	v_mov_b64_e32 v[36:37], s[28:29]
	v_mad_i64_i32 v[30:31], s[4:5], v29, s25, v[36:37]
	v_lshlrev_b32_e32 v194, 1, v28
	v_lshl_add_u64 v[32:33], v[30:31], 0, v[194:195]
	global_load_dwordx4 v[28:31], v[32:33], off offset:3072
	v_add_u32_e32 v134, -2, v27
	v_mad_i64_i32 v[136:137], s[4:5], v134, s25, v[36:37]
	v_lshl_add_u64 v[136:137], v[136:137], 0, v[194:195]
	global_load_dwordx4 v[110:113], v[136:137], off offset:3072
	v_add_co_u32_e32 v32, vcc, 0x1000, v32
	s_nop 1
	v_addc_co_u32_e32 v33, vcc, 0, v33, vcc
	global_load_dwordx4 v[32:35], v[32:33], off offset:1024
	v_add_co_u32_e32 v136, vcc, 0x1000, v136
	s_nop 1
	v_addc_co_u32_e32 v137, vcc, 0, v137, vcc
	global_load_dwordx4 v[130:133], v[136:137], off offset:1024
	s_waitcnt vmcnt(0)
	v_lshlrev_b32_e32 v38, 16, v28
	v_and_b32_e32 v39, 0xffff0000, v28
	v_lshlrev_b32_e32 v28, 16, v29
	v_and_b32_e32 v29, 0xffff0000, v29
	v_lshlrev_b32_e32 v42, 16, v30
	v_and_b32_e32 v43, 0xffff0000, v30
	v_lshlrev_b32_e32 v30, 16, v31
	v_and_b32_e32 v31, 0xffff0000, v31
	v_lshlrev_b32_e32 v40, 16, v32
	v_and_b32_e32 v41, 0xffff0000, v32
	v_lshlrev_b32_e32 v32, 16, v33
	v_and_b32_e32 v33, 0xffff0000, v33
	v_pk_mul_f32 v[50:51], v[28:29], v[32:33]
	v_lshlrev_b32_e32 v44, 16, v34
	v_and_b32_e32 v45, 0xffff0000, v34
	v_lshlrev_b32_e32 v34, 16, v35
	v_and_b32_e32 v35, 0xffff0000, v35
	v_pk_mul_f32 v[46:47], v[30:31], v[34:35]
	v_pk_mul_f32 v[52:53], v[38:39], v[40:41]
	v_pk_mul_f32 v[48:49], v[42:43], v[44:45]
	s_movk_i32 s4, 0x1000
	v_mov_b32_e32 v28, v110
	v_mov_b32_e32 v29, v111
	v_mov_b32_e32 v30, v112
	v_mov_b32_e32 v31, v113
	v_mov_b32_e32 v32, v130
	v_mov_b32_e32 v33, v131
	v_mov_b32_e32 v34, v132
	v_mov_b32_e32 v35, v133
	v_and_b32_e32 v36, 0xffff0000, v28
	v_lshlrev_b32_e32 v37, 16, v28
	v_and_b32_e32 v28, 0xffff0000, v29
	v_lshlrev_b32_e32 v29, 16, v29
	v_lshlrev_b32_e32 v40, 16, v30
	v_and_b32_e32 v41, 0xffff0000, v30
	v_and_b32_e32 v38, 0xffff0000, v32
	v_lshlrev_b32_e32 v39, 16, v32
	v_and_b32_e32 v32, 0xffff0000, v33
	v_lshlrev_b32_e32 v33, 16, v33
	v_lshlrev_b32_e32 v42, 16, v34
	v_and_b32_e32 v43, 0xffff0000, v34
	v_lshlrev_b32_e32 v30, 16, v31
	v_and_b32_e32 v31, 0xffff0000, v31
	v_lshlrev_b32_e32 v34, 16, v35
	v_and_b32_e32 v35, 0xffff0000, v35
	v_pk_mul_f32 v[106:107], v[36:37], v[38:39]
	v_pk_mul_f32 v[38:39], v[28:29], v[32:33]
	v_pk_mul_f32 v[42:43], v[40:41], v[42:43]
	v_pk_mul_f32 v[104:105], v[30:31], v[34:35]
